# early-invalidate lean barrier also at the first (post-P0) grid barrier, behind hipcc's census
# speedup vs baseline: 1.0394x; 1.0029x over previous
; __device__ __forceinline__ unsigned xb_ld(unsigned* p)              { return __hip_atomic_load(p, __ATOMIC_RELAXED, __HIP_MEMORY_SCOPE_AGENT); }
; __device__ __forceinline__ unsigned xb_add(unsigned* p, unsigned v) { return __hip_atomic_fetch_add(p, v, __ATOMIC_RELAXED, __HIP_MEMORY_SCOPE_AGENT); }
; #define XB_SPIN(cond, bar) do { unsigned _sp = 0; while (cond) { __builtin_amdgcn_s_sleep(1); \
;     if ((++_sp & 255u) == 0u) { if (xb_ld(&(bar)[XB_TMO])) break; if (_sp > XB_SPIN_CAP) { atomicAdd(&(bar)[XB_TMO], 1u); break; } } } } while (0)
; __device__ __forceinline__ void xcd_barrier(const XcdBarrier& b) {
;     ...
;         if (nloc == 0u) { xcd_barrier_complete(bar, b.x, nloc, nx); b.st[0] = nloc; b.st[1] = nx; }
;         const unsigned old = xb_add(&bar[XB_XSUB(b.x)], 1u);
;         const unsigned gen = old / nloc;
;         if (old + 1u == (gen + 1u) * nloc) {
;             __builtin_amdgcn_fence(__ATOMIC_RELEASE, "agent");
;             asm volatile("s_waitcnt vmcnt(0)" ::: "memory");
;             const unsigned og = xb_add(&bar[XB_TOP], 1u);
;             const unsigned tg = og / nx;
;             if (og + 1u == (tg + 1u) * nx) xb_add(&bar[XB_TOPGEN], 1u);
;             else XB_SPIN(xb_ld(&bar[XB_TOPGEN]) == tg, bar);
;             __builtin_amdgcn_fence(__ATOMIC_ACQUIRE, "agent");
;             xb_add(&bar[XB_XGEN(b.x)], 1u);
;             asm volatile("s_waitcnt vmcnt(0)" ::: "memory");
;         } else {
;             XB_SPIN(xb_ld(&bar[XB_XGEN(b.x)]) == gen, bar);
;             __builtin_amdgcn_fence(__ATOMIC_ACQUIRE, "agent");
;             asm volatile("s_waitcnt vmcnt(0)" ::: "memory");
;         }
.LBB0_151:
	s_waitcnt lgkmcnt(0)
	v_readfirstlane_b32 s14, v2
	v_readfirstlane_b32 s15, v0
	s_lshl_b32 s4, s3, 8
	s_add_u32 s6, s78, 0x1701400
	s_addc_u32 s7, s79, 0
	s_add_u32 s6, s6, s4
	s_addc_u32 s7, s7, 0
	s_add_u32 s8, s6, 0x1000
	s_addc_u32 s9, s7, 0
	s_add_u32 s10, s78, 0x1703400
	s_addc_u32 s11, s79, 0
	v_mov_b32_e32 v0, 0
	v_mov_b32_e32 v1, 1
	global_atomic_add v2, v0, v1, s[6:7] sc0
	buffer_inv sc1
	s_waitcnt vmcnt(1)
	v_readfirstlane_b32 s4, v2
	s_nop 3
	s_add_i32 s4, s4, 1
	s_cmp_lg_u32 s4, s14
	s_cbranch_scc1 .Lxb_local_p
	buffer_wbl2 sc1
	s_waitcnt vmcnt(0)
	global_atomic_add v0, v1, s[10:11]
	s_mov_b32 s4, 0
.Lxb_top_p:
	global_load_dword v2, v0, s[10:11] sc1
	s_waitcnt vmcnt(0)
	v_readfirstlane_b32 s5, v2
	s_nop 3
	s_cmp_ge_u32 s5, s15
	s_cbranch_scc1 .Lxb_top_p_done
	s_sleep 1
	s_add_i32 s4, s4, 1
	s_cmp_lt_u32 s4, 0x40000
	s_cbranch_scc1 .Lxb_top_p
.Lxb_top_p_done:
	global_atomic_add v0, v1, s[8:9]
	s_branch .LBB0_187
.Lxb_local_p:
	s_mov_b32 s4, 0
.Lxb_gen_p:
	global_load_dword v2, v0, s[8:9] sc1
	s_waitcnt vmcnt(0)
	v_readfirstlane_b32 s5, v2
	s_nop 3
	s_cmp_lg_u32 s5, 0
	s_cbranch_scc1 .Lxb_gen_p_done
	s_sleep 1
	s_add_i32 s4, s4, 1
	s_cmp_lt_u32 s4, 0x40000
	s_cbranch_scc1 .Lxb_gen_p
.Lxb_gen_p_done:
	s_branch .LBB0_187
	s_mov_b64 s[6:7], exec
	s_lshl_b32 s3, s3, 8
	v_readlane_b32 s4, v253, 0
	v_mbcnt_lo_u32_b32 v1, s6, 0
	v_readlane_b32 s5, v253, 1
	s_add_u32 s4, s4, s3
	v_mbcnt_hi_u32_b32 v1, s7, v1
	s_addc_u32 s5, s5, 0
	v_cmp_eq_u32_e32 vcc, 0, v1
	s_and_saveexec_b64 s[8:9], vcc
	s_cbranch_execz .LBB0_153
	s_bcnt1_i32_b64 s3, s[6:7]
	v_mov_b32_e32 v3, 0x1000
	v_mov_b32_e32 v4, s3
	global_atomic_add v3, v3, v4, s[4:5] offset:1024 sc0
